# weight conversion: 8 W-row loads (+8 k-scale loads) per trip issued together with one wait instead of 8-16 serialized round trips
# speedup vs baseline: 1.0036x; 1.0036x over previous
; #define LAS __attribute__((address_space(3)))
; __device__ __forceinline__ void conv_item(const float* W, int K, int N, int Np, bf16_t* WT, const float* kscale, int mapmode, LAS float* scr, int item, int lane) {
;     const int nblk = Np / 64, kb = item / nblk, nb = item % nblk, k0 = 64 * kb, n0 = 64 * nb;
;     int src0 = n0;
;     if (mapmode == 1) { const int tl = n0 >> 8, i = n0 & 255; src0 = (i < 128) ? (128 * tl + i) : (FFH + 128 * tl + (i - 128)); }
;     const int c4 = 4 * (lane & 15);
;     const bool valid = (mapmode == 1) || (n0 + c4 < N);
; #pragma unroll 8
;     for (int j = 0; j < 16; ++j) { const int kk = 4 * j + (lane >> 4);
;         f32x4 v = (f32x4){0.f, 0.f, 0.f, 0.f};
;         if (valid) { v = *(const f32x4*)(W + (size_t)(k0 + kk) * N + src0 + c4); if (kscale) v = v * kscale[k0 + kk]; }
;         LAS float* d = scr + kk * 65 + c4; d[0] = v[0]; d[1] = v[1]; d[2] = v[2]; d[3] = v[3]; }
.LBB0_597:
	s_or_b64 exec, exec, s[50:51]
	v_add_u32_e32 v6, 0x1c70, v32
	s_add_i32 s52, s52, 32
	s_nop 0
	ds_write2_b32 v6, v2, v3 offset1:1
	v_add_u32_e32 v2, 0x1c78, v32
	v_add_u32_e32 v32, 0x2080, v32
	s_cmp_lg_u32 s52, 64
	v_lshl_add_u64 v[20:21], v[20:21], 0, s[34:35]
	ds_write2_b32 v2, v4, v5 offset1:1
	s_cbranch_scc0 .LBB0_590
.LBB0_598:
	v_cndmask_b32_e64 v3, 0, 1, s[94:95]
	v_mov_b32_e32 v2, 0
	v_cmp_ne_u32_e64 s[0:1], 1, v3
	s_and_saveexec_b64 s[50:51], s[48:49]
	s_cbranch_execz .Lcv_skip
	v_add_u32_e32 v33, s52, v0
	v_mad_u64_u32 v[34:35], s[54:55], v33, s21, 0
	v_ashrrev_i32_e32 v36, 31, v33
	v_mov_b32_e32 v38, v35
	v_mad_u64_u32 v[38:39], s[54:55], v36, s21, v[38:39]
	v_mov_b32_e32 v35, v38
	v_lshl_add_u64 v[34:35], v[34:35], 2, v[18:19]
	global_load_dwordx4 v[40:43], v[34:35], off
	v_add3_u32 v33, v0, s52, 4
	v_mad_u64_u32 v[34:35], s[54:55], v33, s21, 0
	v_ashrrev_i32_e32 v36, 31, v33
	v_mov_b32_e32 v38, v35
	v_mad_u64_u32 v[38:39], s[54:55], v36, s21, v[38:39]
	v_mov_b32_e32 v35, v38
	v_lshl_add_u64 v[34:35], v[34:35], 2, v[18:19]
	global_load_dwordx4 v[44:47], v[34:35], off
	v_add3_u32 v33, v0, s52, 8
	v_mad_u64_u32 v[34:35], s[54:55], v33, s21, 0
	v_ashrrev_i32_e32 v36, 31, v33
	v_mov_b32_e32 v38, v35
	v_mad_u64_u32 v[38:39], s[54:55], v36, s21, v[38:39]
	v_mov_b32_e32 v35, v38
	v_lshl_add_u64 v[34:35], v[34:35], 2, v[18:19]
	global_load_dwordx4 v[48:51], v[34:35], off
	v_add3_u32 v33, v0, s52, 12
	v_mad_u64_u32 v[34:35], s[54:55], v33, s21, 0
	v_ashrrev_i32_e32 v36, 31, v33
	v_mov_b32_e32 v38, v35
	v_mad_u64_u32 v[38:39], s[54:55], v36, s21, v[38:39]
	v_mov_b32_e32 v35, v38
	v_lshl_add_u64 v[34:35], v[34:35], 2, v[18:19]
	global_load_dwordx4 v[52:55], v[34:35], off
	v_add3_u32 v33, v0, s52, 16
	v_mad_u64_u32 v[34:35], s[54:55], v33, s21, 0
	v_ashrrev_i32_e32 v36, 31, v33
	v_mov_b32_e32 v38, v35
	v_mad_u64_u32 v[38:39], s[54:55], v36, s21, v[38:39]
	v_mov_b32_e32 v35, v38
	v_lshl_add_u64 v[34:35], v[34:35], 2, v[18:19]
	global_load_dwordx4 v[56:59], v[34:35], off
	v_add3_u32 v33, v0, s52, 20
	v_mad_u64_u32 v[34:35], s[54:55], v33, s21, 0
	v_ashrrev_i32_e32 v36, 31, v33
	v_mov_b32_e32 v38, v35
	v_mad_u64_u32 v[38:39], s[54:55], v36, s21, v[38:39]
	v_mov_b32_e32 v35, v38
	v_lshl_add_u64 v[34:35], v[34:35], 2, v[18:19]
	global_load_dwordx4 v[60:63], v[34:35], off
	v_add3_u32 v33, v0, s52, 24
	v_mad_u64_u32 v[34:35], s[54:55], v33, s21, 0
	v_ashrrev_i32_e32 v36, 31, v33
	v_mov_b32_e32 v38, v35
	v_mad_u64_u32 v[38:39], s[54:55], v36, s21, v[38:39]
	v_mov_b32_e32 v35, v38
	v_lshl_add_u64 v[34:35], v[34:35], 2, v[18:19]
	global_load_dwordx4 v[64:67], v[34:35], off
	v_add3_u32 v33, v0, s52, 28
	v_mad_u64_u32 v[34:35], s[54:55], v33, s21, 0
	v_ashrrev_i32_e32 v36, 31, v33
	v_mov_b32_e32 v38, v35
	v_mad_u64_u32 v[38:39], s[54:55], v36, s21, v[38:39]
	v_mov_b32_e32 v35, v38
	v_lshl_add_u64 v[34:35], v[34:35], 2, v[18:19]
	global_load_dwordx4 v[68:71], v[34:35], off
	s_and_b64 vcc, exec, s[0:1]
	s_cbranch_vccnz .Lcv_skip
	global_load_dword v72, v[20:21], off offset:-112
	global_load_dword v73, v[20:21], off offset:-96
	global_load_dword v74, v[20:21], off offset:-80
	global_load_dword v75, v[20:21], off offset:-64
	global_load_dword v76, v[20:21], off offset:-48
	global_load_dword v77, v[20:21], off offset:-32
	global_load_dword v78, v[20:21], off offset:-16
	global_load_dword v79, v[20:21], off
.Lcv_skip:
	s_or_b64 exec, exec, s[50:51]
	s_waitcnt vmcnt(0)
	v_mov_b32_e32 v4, 0
	v_mov_b32_e32 v5, 0
	v_mov_b32_e32 v6, 0
	v_mov_b32_e32 v7, 0
	s_and_saveexec_b64 s[50:51], s[48:49]
	s_cbranch_execz .LBB0_601
	v_add_u32_e32 v22, s52, v0
	v_mad_u64_u32 v[4:5], s[54:55], v22, s21, 0
	v_ashrrev_i32_e32 v23, 31, v22
	v_mov_b32_e32 v6, v5
	v_mad_u64_u32 v[6:7], s[54:55], v23, s21, v[6:7]
	v_mov_b32_e32 v5, v6
	v_lshl_add_u64 v[4:5], v[4:5], 2, v[18:19]
	v_mov_b32_e32 v4, v40
	v_mov_b32_e32 v5, v41
	v_mov_b32_e32 v6, v42
	v_mov_b32_e32 v7, v43
	s_and_b64 vcc, exec, s[0:1]
	s_cbranch_vccnz .LBB0_601
	v_lshl_add_u64 v[22:23], v[22:23], 2, s[90:91]
	v_mov_b32_e32 v22, v72
	v_pk_mul_f32 v[6:7], v[6:7], v[22:23] op_sel_hi:[1,0]
	v_pk_mul_f32 v[4:5], v[4:5], v[22:23] op_sel_hi:[1,0]
.LBB0_601:
	s_or_b64 exec, exec, s[50:51]
	s_nop 0
	ds_write2_b32 v32, v4, v5 offset1:1
	ds_write2_b32 v32, v6, v7 offset0:2 offset1:3
	v_mov_b32_e32 v3, 0
	v_mov_b32_e32 v4, 0
	v_mov_b32_e32 v5, 0
	s_and_saveexec_b64 s[50:51], s[48:49]
	s_cbranch_execz .LBB0_604
	v_add3_u32 v2, v0, s52, 4
	v_ashrrev_i32_e32 v5, 31, v2
	v_mad_u64_u32 v[2:3], s[54:55], v2, s21, 0
	v_mov_b32_e32 v4, v3
	v_mad_u64_u32 v[4:5], s[54:55], v5, s21, v[4:5]
	v_mov_b32_e32 v3, v4
	v_lshl_add_u64 v[2:3], v[2:3], 2, v[18:19]
	v_mov_b32_e32 v2, v44
	v_mov_b32_e32 v3, v45
	v_mov_b32_e32 v4, v46
	v_mov_b32_e32 v5, v47
	s_and_b64 vcc, exec, s[0:1]
	s_cbranch_vccnz .LBB0_604
	v_mov_b32_e32 v6, v73
	v_pk_mul_f32 v[4:5], v[4:5], v[6:7] op_sel_hi:[1,0]
	v_pk_mul_f32 v[2:3], v[2:3], v[6:7] op_sel_hi:[1,0]
; #define LAS __attribute__((address_space(3)))
; __device__ __forceinline__ void conv_item(const float* W, int K, int N, int Np, bf16_t* WT, const float* kscale, int mapmode, LAS float* scr, int item, int lane) {
;     ...
; #pragma unroll 8
;     for (int j = 0; j < 16; ++j) { const int kk = 4 * j + (lane >> 4);
;         f32x4 v = (f32x4){0.f, 0.f, 0.f, 0.f};
;         if (valid) { v = *(const f32x4*)(W + (size_t)(k0 + kk) * N + src0 + c4); if (kscale) v = v * kscale[k0 + kk]; }
;         LAS float* d = scr + kk * 65 + c4; d[0] = v[0]; d[1] = v[1]; d[2] = v[2]; d[3] = v[3]; }
.LBB0_604:
	s_or_b64 exec, exec, s[50:51]
	v_add_u32_e32 v6, 0x410, v32
	s_nop 0
	ds_write2_b32 v6, v2, v3 offset1:1
	v_add_u32_e32 v2, 0x418, v32
	ds_write2_b32 v2, v4, v5 offset1:1
	v_mov_b32_e32 v2, 0
	v_mov_b32_e32 v4, 0
	v_mov_b32_e32 v5, 0
	v_mov_b32_e32 v6, 0
	v_mov_b32_e32 v7, 0
	s_and_saveexec_b64 s[50:51], s[48:49]
	s_cbranch_execz .LBB0_607
	v_add3_u32 v3, v0, s52, 8
	v_mad_u64_u32 v[4:5], s[54:55], v3, s21, 0
	v_ashrrev_i32_e32 v7, 31, v3
	v_mov_b32_e32 v6, v5
	v_mad_u64_u32 v[6:7], s[54:55], v7, s21, v[6:7]
	v_mov_b32_e32 v5, v6
	v_lshl_add_u64 v[4:5], v[4:5], 2, v[18:19]
	v_mov_b32_e32 v4, v48
	v_mov_b32_e32 v5, v49
	v_mov_b32_e32 v6, v50
	v_mov_b32_e32 v7, v51
	s_and_b64 vcc, exec, s[0:1]
	s_cbranch_vccnz .LBB0_607
	v_mov_b32_e32 v22, v74
	v_pk_mul_f32 v[6:7], v[6:7], v[22:23] op_sel_hi:[1,0]
	v_pk_mul_f32 v[4:5], v[4:5], v[22:23] op_sel_hi:[1,0]
.LBB0_607:
	s_or_b64 exec, exec, s[50:51]
	v_add_u32_e32 v3, 0x820, v32
	s_nop 0
	ds_write2_b32 v3, v4, v5 offset1:1
	v_add_u32_e32 v3, 0x828, v32
	ds_write2_b32 v3, v6, v7 offset1:1
	v_mov_b32_e32 v3, 0
	v_mov_b32_e32 v4, 0
	v_mov_b32_e32 v5, 0
	s_and_saveexec_b64 s[50:51], s[48:49]
	s_cbranch_execz .LBB0_610
	v_add3_u32 v2, v0, s52, 12
	v_ashrrev_i32_e32 v5, 31, v2
	v_mad_u64_u32 v[2:3], s[54:55], v2, s21, 0
	v_mov_b32_e32 v4, v3
	v_mad_u64_u32 v[4:5], s[54:55], v5, s21, v[4:5]
	v_mov_b32_e32 v3, v4
	v_lshl_add_u64 v[2:3], v[2:3], 2, v[18:19]
	v_mov_b32_e32 v2, v52
	v_mov_b32_e32 v3, v53
	v_mov_b32_e32 v4, v54
	v_mov_b32_e32 v5, v55
	s_and_b64 vcc, exec, s[0:1]
	s_cbranch_vccnz .LBB0_610
	v_mov_b32_e32 v6, v75
	v_pk_mul_f32 v[4:5], v[4:5], v[6:7] op_sel_hi:[1,0]
	v_pk_mul_f32 v[2:3], v[2:3], v[6:7] op_sel_hi:[1,0]
.LBB0_610:
	s_or_b64 exec, exec, s[50:51]
	v_add_u32_e32 v6, 0xc30, v32
	s_nop 0
	ds_write2_b32 v6, v2, v3 offset1:1
	v_add_u32_e32 v2, 0xc38, v32
	ds_write2_b32 v2, v4, v5 offset1:1
	v_mov_b32_e32 v2, 0
	v_mov_b32_e32 v4, 0
	v_mov_b32_e32 v5, 0
	v_mov_b32_e32 v6, 0
	v_mov_b32_e32 v7, 0
	s_and_saveexec_b64 s[50:51], s[48:49]
	s_cbranch_execz .LBB0_613
	v_add3_u32 v3, v0, s52, 16
	v_mad_u64_u32 v[4:5], s[54:55], v3, s21, 0
	v_ashrrev_i32_e32 v7, 31, v3
	v_mov_b32_e32 v6, v5
	v_mad_u64_u32 v[6:7], s[54:55], v7, s21, v[6:7]
	v_mov_b32_e32 v5, v6
	v_lshl_add_u64 v[4:5], v[4:5], 2, v[18:19]
	v_mov_b32_e32 v4, v56
	v_mov_b32_e32 v5, v57
	v_mov_b32_e32 v6, v58
	v_mov_b32_e32 v7, v59
	s_and_b64 vcc, exec, s[0:1]
	s_cbranch_vccnz .LBB0_613
	v_mov_b32_e32 v22, v76
	v_pk_mul_f32 v[6:7], v[6:7], v[22:23] op_sel_hi:[1,0]
	v_pk_mul_f32 v[4:5], v[4:5], v[22:23] op_sel_hi:[1,0]
.LBB0_613:
	s_or_b64 exec, exec, s[50:51]
	v_add_u32_e32 v3, 0x1040, v32
	s_nop 0
	ds_write2_b32 v3, v4, v5 offset1:1
	v_add_u32_e32 v3, 0x1048, v32
	ds_write2_b32 v3, v6, v7 offset1:1
	v_mov_b32_e32 v3, 0
	v_mov_b32_e32 v4, 0
	v_mov_b32_e32 v5, 0
	s_and_saveexec_b64 s[50:51], s[48:49]
	s_cbranch_execz .LBB0_616
	v_add3_u32 v2, v0, s52, 20
	v_ashrrev_i32_e32 v5, 31, v2
	v_mad_u64_u32 v[2:3], s[54:55], v2, s21, 0
	v_mov_b32_e32 v4, v3
	v_mad_u64_u32 v[4:5], s[54:55], v5, s21, v[4:5]
	v_mov_b32_e32 v3, v4
	v_lshl_add_u64 v[2:3], v[2:3], 2, v[18:19]
	v_mov_b32_e32 v2, v60
	v_mov_b32_e32 v3, v61
	v_mov_b32_e32 v4, v62
	v_mov_b32_e32 v5, v63
	s_and_b64 vcc, exec, s[0:1]
	s_cbranch_vccnz .LBB0_616
	v_mov_b32_e32 v6, v77
	v_pk_mul_f32 v[4:5], v[4:5], v[6:7] op_sel_hi:[1,0]
	v_pk_mul_f32 v[2:3], v[2:3], v[6:7] op_sel_hi:[1,0]
.LBB0_616:
	s_or_b64 exec, exec, s[50:51]
	v_add_u32_e32 v6, 0x1450, v32
	s_nop 0
	ds_write2_b32 v6, v2, v3 offset1:1
	v_add_u32_e32 v2, 0x1458, v32
	ds_write2_b32 v2, v4, v5 offset1:1
	v_mov_b32_e32 v2, 0
	v_mov_b32_e32 v4, 0
	v_mov_b32_e32 v5, 0
	v_mov_b32_e32 v6, 0
	v_mov_b32_e32 v7, 0
	s_and_saveexec_b64 s[50:51], s[48:49]
	s_cbranch_execz .LBB0_619
	v_add3_u32 v3, v0, s52, 24
	v_mad_u64_u32 v[4:5], s[54:55], v3, s21, 0
	v_ashrrev_i32_e32 v7, 31, v3
	v_mov_b32_e32 v6, v5
	v_mad_u64_u32 v[6:7], s[54:55], v7, s21, v[6:7]
	v_mov_b32_e32 v5, v6
	v_lshl_add_u64 v[4:5], v[4:5], 2, v[18:19]
	v_mov_b32_e32 v4, v64
	v_mov_b32_e32 v5, v65
	v_mov_b32_e32 v6, v66
	v_mov_b32_e32 v7, v67
	s_and_b64 vcc, exec, s[0:1]
	s_cbranch_vccnz .LBB0_619
	v_mov_b32_e32 v22, v78
	v_pk_mul_f32 v[6:7], v[6:7], v[22:23] op_sel_hi:[1,0]
	v_pk_mul_f32 v[4:5], v[4:5], v[22:23] op_sel_hi:[1,0]
.LBB0_619:
	s_or_b64 exec, exec, s[50:51]
	v_add_u32_e32 v3, 0x1860, v32
	s_nop 0
	ds_write2_b32 v3, v4, v5 offset1:1
	v_add_u32_e32 v3, 0x1868, v32
	ds_write2_b32 v3, v6, v7 offset1:1
	v_mov_b32_e32 v3, 0
	v_mov_b32_e32 v4, 0
	v_mov_b32_e32 v5, 0
	s_and_saveexec_b64 s[50:51], s[48:49]
	s_cbranch_execz .LBB0_597
	v_add3_u32 v2, v0, s52, 28
	v_ashrrev_i32_e32 v5, 31, v2
	v_mad_u64_u32 v[2:3], s[54:55], v2, s21, 0
	v_mov_b32_e32 v4, v3
	v_mad_u64_u32 v[4:5], s[54:55], v5, s21, v[4:5]
	v_mov_b32_e32 v3, v4
	v_lshl_add_u64 v[2:3], v[2:3], 2, v[18:19]
	v_mov_b32_e32 v2, v68
	v_mov_b32_e32 v3, v69
	v_mov_b32_e32 v4, v70
	v_mov_b32_e32 v5, v71
	s_and_b64 vcc, exec, s[0:1]
	s_cbranch_vccnz .LBB0_597
	v_mov_b32_e32 v6, v79
	v_pk_mul_f32 v[4:5], v[4:5], v[6:7] op_sel_hi:[1,0]
	v_pk_mul_f32 v[2:3], v[2:3], v[6:7] op_sel_hi:[1,0]
	s_branch .LBB0_597
